# UP GEMM: hand-written epilogue (row-rstd loads issued up front, no store-dependent waits, permlane16-swapped dwordx4 stores), K-loop covers all k-steps
# speedup vs baseline: 1.0192x; 1.0192x over previous
.Lgm0_loop:
	v_add_u32_e32 v248, s30, v155
	v_add_u32_e32 v249, s30, v160
	v_mfma_f32_16x16x32_bf16 v[128:131], v[212:215], v[186:189], v[128:131]
	ds_read_b128 v[0:3], v248
	v_mfma_f32_16x16x32_bf16 v[96:99], v[212:215], v[190:193], v[96:99]
	ds_read_b128 v[16:19], v249 offset:8192
	v_mfma_f32_16x16x32_bf16 v[108:111], v[212:215], v[194:197], v[108:111]
	ds_read_b128 v[4:7], v248 offset:1024
	v_mfma_f32_16x16x32_bf16 v[132:135], v[212:215], v[208:211], v[132:135]
	ds_read_b128 v[20:23], v249 offset:9216
	v_mfma_f32_16x16x32_bf16 v[116:119], v[216:219], v[186:189], v[116:119]
	ds_read_b128 v[8:11], v248 offset:2048
	v_mfma_f32_16x16x32_bf16 v[92:95], v[216:219], v[190:193], v[92:95]
	ds_read_b128 v[162:165], v249 offset:10240
	v_mfma_f32_16x16x32_bf16 v[112:115], v[216:219], v[194:197], v[112:115]
	ds_read_b128 v[12:15], v248 offset:3072
	v_mfma_f32_16x16x32_bf16 v[136:139], v[216:219], v[208:211], v[136:139]
	ds_read_b128 v[166:169], v249 offset:11264
	v_mfma_f32_16x16x32_bf16 v[104:107], v[220:223], v[186:189], v[104:107]
	ds_read_b128 v[170:173], v249 offset:12288
	v_mfma_f32_16x16x32_bf16 v[88:91], v[220:223], v[190:193], v[88:91]
	ds_read_b128 v[174:177], v249 offset:13312
	v_mfma_f32_16x16x32_bf16 v[120:123], v[220:223], v[194:197], v[120:123]
	ds_read_b128 v[178:181], v249 offset:14336
	v_mfma_f32_16x16x32_bf16 v[140:143], v[220:223], v[208:211], v[140:143]
	ds_read_b128 v[182:185], v249 offset:15360
	s_add_u32 m0, s25, s24
	v_mfma_f32_16x16x32_bf16 v[100:103], v[224:227], v[186:189], v[100:103]
	global_load_lds_dwordx4 v244, s[26:27]
	v_mfma_f32_16x16x32_bf16 v[84:87], v[224:227], v[190:193], v[84:87]
	v_mfma_f32_16x16x32_bf16 v[124:127], v[224:227], v[194:197], v[124:127]
	s_add_u32 m0, m0, 0x1000
	v_mfma_f32_16x16x32_bf16 v[144:147], v[224:227], v[208:211], v[144:147]
	global_load_lds_dwordx4 v245, s[26:27]
	v_mfma_f32_16x16x32_bf16 v[52:55], v[228:231], v[186:189], v[52:55]
	v_mfma_f32_16x16x32_bf16 v[36:39], v[228:231], v[190:193], v[36:39]
	s_add_u32 m0, m0, 0x1000
	v_mfma_f32_16x16x32_bf16 v[64:67], v[228:231], v[194:197], v[64:67]
	global_load_lds_dwordx4 v244, s[28:29]
	v_mfma_f32_16x16x32_bf16 v[76:79], v[228:231], v[208:211], v[76:79]
	v_mfma_f32_16x16x32_bf16 v[48:51], v[232:235], v[186:189], v[48:51]
	s_add_u32 m0, m0, 0x1000
	v_mfma_f32_16x16x32_bf16 v[32:35], v[232:235], v[190:193], v[32:35]
	global_load_lds_dwordx4 v245, s[28:29]
	v_mfma_f32_16x16x32_bf16 v[68:71], v[232:235], v[194:197], v[68:71]
	v_mfma_f32_16x16x32_bf16 v[72:75], v[232:235], v[208:211], v[72:75]
	s_add_u32 m0, m0, 0x1000
	v_mfma_f32_16x16x32_bf16 v[44:47], v[236:239], v[186:189], v[44:47]
	global_load_lds_dwordx4 v246, s[28:29]
	v_mfma_f32_16x16x32_bf16 v[28:31], v[236:239], v[190:193], v[28:31]
	v_mfma_f32_16x16x32_bf16 v[80:83], v[236:239], v[194:197], v[80:83]
	s_add_u32 m0, m0, 0x1000
	v_mfma_f32_16x16x32_bf16 v[60:63], v[236:239], v[208:211], v[60:63]
	global_load_lds_dwordx4 v247, s[28:29]
	v_mfma_f32_16x16x32_bf16 v[40:43], v[240:243], v[186:189], v[40:43]
	v_mfma_f32_16x16x32_bf16 v[24:27], v[240:243], v[190:193], v[24:27]
	v_mfma_f32_16x16x32_bf16 v[56:59], v[240:243], v[194:197], v[56:59]
	v_mfma_f32_16x16x32_bf16 v[148:151], v[240:243], v[208:211], v[148:151]
	s_add_u32 s26, s26, 64
	s_addc_u32 s27, s27, 0
	s_add_u32 s28, s28, 64
	s_addc_u32 s29, s29, 0
	s_add_u32 s25, s25, 24576
	s_cmp_eq_u32 s25, 73728
	s_cselect_b32 s25, 0, s25
	s_add_u32 s30, s30, 24576
	s_cmp_eq_u32 s30, 73728
	s_cselect_b32 s30, 0, s30
	s_waitcnt vmcnt(6)
	s_waitcnt lgkmcnt(0)
	s_barrier
	v_add_u32_e32 v248, s30, v155
	v_add_u32_e32 v249, s30, v160
	v_mfma_f32_16x16x32_bf16 v[128:131], v[16:19], v[0:3], v[128:131]
	ds_read_b128 v[186:189], v248
	v_mfma_f32_16x16x32_bf16 v[96:99], v[16:19], v[4:7], v[96:99]
	ds_read_b128 v[212:215], v249 offset:8192
	v_mfma_f32_16x16x32_bf16 v[108:111], v[16:19], v[8:11], v[108:111]
	ds_read_b128 v[190:193], v248 offset:1024
	v_mfma_f32_16x16x32_bf16 v[132:135], v[16:19], v[12:15], v[132:135]
	ds_read_b128 v[216:219], v249 offset:9216
	v_mfma_f32_16x16x32_bf16 v[116:119], v[20:23], v[0:3], v[116:119]
	ds_read_b128 v[194:197], v248 offset:2048
	v_mfma_f32_16x16x32_bf16 v[92:95], v[20:23], v[4:7], v[92:95]
	ds_read_b128 v[220:223], v249 offset:10240
	v_mfma_f32_16x16x32_bf16 v[112:115], v[20:23], v[8:11], v[112:115]
	ds_read_b128 v[208:211], v248 offset:3072
	v_mfma_f32_16x16x32_bf16 v[136:139], v[20:23], v[12:15], v[136:139]
	ds_read_b128 v[224:227], v249 offset:11264
	v_mfma_f32_16x16x32_bf16 v[104:107], v[162:165], v[0:3], v[104:107]
	ds_read_b128 v[228:231], v249 offset:12288
	v_mfma_f32_16x16x32_bf16 v[88:91], v[162:165], v[4:7], v[88:91]
	ds_read_b128 v[232:235], v249 offset:13312
	v_mfma_f32_16x16x32_bf16 v[120:123], v[162:165], v[8:11], v[120:123]
	ds_read_b128 v[236:239], v249 offset:14336
	v_mfma_f32_16x16x32_bf16 v[140:143], v[162:165], v[12:15], v[140:143]
	ds_read_b128 v[240:243], v249 offset:15360
	s_add_u32 m0, s25, s24
	v_mfma_f32_16x16x32_bf16 v[100:103], v[166:169], v[0:3], v[100:103]
	global_load_lds_dwordx4 v244, s[26:27]
	v_mfma_f32_16x16x32_bf16 v[84:87], v[166:169], v[4:7], v[84:87]
	v_mfma_f32_16x16x32_bf16 v[124:127], v[166:169], v[8:11], v[124:127]
	s_add_u32 m0, m0, 0x1000
	v_mfma_f32_16x16x32_bf16 v[144:147], v[166:169], v[12:15], v[144:147]
	global_load_lds_dwordx4 v245, s[26:27]
	v_mfma_f32_16x16x32_bf16 v[52:55], v[170:173], v[0:3], v[52:55]
	v_mfma_f32_16x16x32_bf16 v[36:39], v[170:173], v[4:7], v[36:39]
	s_add_u32 m0, m0, 0x1000
	v_mfma_f32_16x16x32_bf16 v[64:67], v[170:173], v[8:11], v[64:67]
	global_load_lds_dwordx4 v244, s[28:29]
	v_mfma_f32_16x16x32_bf16 v[76:79], v[170:173], v[12:15], v[76:79]
	v_mfma_f32_16x16x32_bf16 v[48:51], v[174:177], v[0:3], v[48:51]
	s_add_u32 m0, m0, 0x1000
	v_mfma_f32_16x16x32_bf16 v[32:35], v[174:177], v[4:7], v[32:35]
	global_load_lds_dwordx4 v245, s[28:29]
	v_mfma_f32_16x16x32_bf16 v[68:71], v[174:177], v[8:11], v[68:71]
	v_mfma_f32_16x16x32_bf16 v[72:75], v[174:177], v[12:15], v[72:75]
	s_add_u32 m0, m0, 0x1000
	v_mfma_f32_16x16x32_bf16 v[44:47], v[178:181], v[0:3], v[44:47]
	global_load_lds_dwordx4 v246, s[28:29]
	v_mfma_f32_16x16x32_bf16 v[28:31], v[178:181], v[4:7], v[28:31]
	v_mfma_f32_16x16x32_bf16 v[80:83], v[178:181], v[8:11], v[80:83]
	s_add_u32 m0, m0, 0x1000
	v_mfma_f32_16x16x32_bf16 v[60:63], v[178:181], v[12:15], v[60:63]
	global_load_lds_dwordx4 v247, s[28:29]
	v_mfma_f32_16x16x32_bf16 v[40:43], v[182:185], v[0:3], v[40:43]
	v_mfma_f32_16x16x32_bf16 v[24:27], v[182:185], v[4:7], v[24:27]
	v_mfma_f32_16x16x32_bf16 v[56:59], v[182:185], v[8:11], v[56:59]
	v_mfma_f32_16x16x32_bf16 v[148:151], v[182:185], v[12:15], v[148:151]
	s_add_u32 s26, s26, 64
	s_addc_u32 s27, s27, 0
	s_add_u32 s28, s28, 64
	s_addc_u32 s29, s29, 0
	s_add_u32 s25, s25, 24576
	s_cmp_eq_u32 s25, 73728
	s_cselect_b32 s25, 0, s25
	s_add_u32 s30, s30, 24576
	s_cmp_eq_u32 s30, 73728
	s_cselect_b32 s30, 0, s30
	s_waitcnt vmcnt(6)
	s_waitcnt lgkmcnt(0)
	s_barrier
	s_sub_u32 s31, s31, 1
	s_cmp_lg_u32 s31, 0
	s_cbranch_scc1 .Lgm0_loop
	v_add_u32_e32 v248, s30, v155
	v_add_u32_e32 v249, s30, v160
	v_mfma_f32_16x16x32_bf16 v[128:131], v[212:215], v[186:189], v[128:131]
	ds_read_b128 v[0:3], v248
	v_mfma_f32_16x16x32_bf16 v[96:99], v[212:215], v[190:193], v[96:99]
	ds_read_b128 v[16:19], v249 offset:8192
	v_mfma_f32_16x16x32_bf16 v[108:111], v[212:215], v[194:197], v[108:111]
	ds_read_b128 v[4:7], v248 offset:1024
	v_mfma_f32_16x16x32_bf16 v[132:135], v[212:215], v[208:211], v[132:135]
	ds_read_b128 v[20:23], v249 offset:9216
	v_mfma_f32_16x16x32_bf16 v[116:119], v[216:219], v[186:189], v[116:119]
	ds_read_b128 v[8:11], v248 offset:2048
	v_mfma_f32_16x16x32_bf16 v[92:95], v[216:219], v[190:193], v[92:95]
	ds_read_b128 v[162:165], v249 offset:10240
	v_mfma_f32_16x16x32_bf16 v[112:115], v[216:219], v[194:197], v[112:115]
	ds_read_b128 v[12:15], v248 offset:3072
	v_mfma_f32_16x16x32_bf16 v[136:139], v[216:219], v[208:211], v[136:139]
	ds_read_b128 v[166:169], v249 offset:11264
	v_mfma_f32_16x16x32_bf16 v[104:107], v[220:223], v[186:189], v[104:107]
	ds_read_b128 v[170:173], v249 offset:12288
	v_mfma_f32_16x16x32_bf16 v[88:91], v[220:223], v[190:193], v[88:91]
	ds_read_b128 v[174:177], v249 offset:13312
	v_mfma_f32_16x16x32_bf16 v[120:123], v[220:223], v[194:197], v[120:123]
	ds_read_b128 v[178:181], v249 offset:14336
	v_mfma_f32_16x16x32_bf16 v[140:143], v[220:223], v[208:211], v[140:143]
	ds_read_b128 v[182:185], v249 offset:15360
	s_add_u32 m0, s25, s24
	v_mfma_f32_16x16x32_bf16 v[100:103], v[224:227], v[186:189], v[100:103]
	global_load_lds_dwordx4 v244, s[26:27]
	v_mfma_f32_16x16x32_bf16 v[84:87], v[224:227], v[190:193], v[84:87]
	v_mfma_f32_16x16x32_bf16 v[124:127], v[224:227], v[194:197], v[124:127]
	s_add_u32 m0, m0, 0x1000
	v_mfma_f32_16x16x32_bf16 v[144:147], v[224:227], v[208:211], v[144:147]
	global_load_lds_dwordx4 v245, s[26:27]
	v_mfma_f32_16x16x32_bf16 v[52:55], v[228:231], v[186:189], v[52:55]
	v_mfma_f32_16x16x32_bf16 v[36:39], v[228:231], v[190:193], v[36:39]
	s_add_u32 m0, m0, 0x1000
	v_mfma_f32_16x16x32_bf16 v[64:67], v[228:231], v[194:197], v[64:67]
	global_load_lds_dwordx4 v244, s[28:29]
	v_mfma_f32_16x16x32_bf16 v[76:79], v[228:231], v[208:211], v[76:79]
	v_mfma_f32_16x16x32_bf16 v[48:51], v[232:235], v[186:189], v[48:51]
	s_add_u32 m0, m0, 0x1000
	v_mfma_f32_16x16x32_bf16 v[32:35], v[232:235], v[190:193], v[32:35]
	global_load_lds_dwordx4 v245, s[28:29]
	v_mfma_f32_16x16x32_bf16 v[68:71], v[232:235], v[194:197], v[68:71]
	v_mfma_f32_16x16x32_bf16 v[72:75], v[232:235], v[208:211], v[72:75]
	s_add_u32 m0, m0, 0x1000
	v_mfma_f32_16x16x32_bf16 v[44:47], v[236:239], v[186:189], v[44:47]
	global_load_lds_dwordx4 v246, s[28:29]
	v_mfma_f32_16x16x32_bf16 v[28:31], v[236:239], v[190:193], v[28:31]
	v_mfma_f32_16x16x32_bf16 v[80:83], v[236:239], v[194:197], v[80:83]
	s_add_u32 m0, m0, 0x1000
	v_mfma_f32_16x16x32_bf16 v[60:63], v[236:239], v[208:211], v[60:63]
	global_load_lds_dwordx4 v247, s[28:29]
	v_mfma_f32_16x16x32_bf16 v[40:43], v[240:243], v[186:189], v[40:43]
	v_mfma_f32_16x16x32_bf16 v[24:27], v[240:243], v[190:193], v[24:27]
	v_mfma_f32_16x16x32_bf16 v[56:59], v[240:243], v[194:197], v[56:59]
	v_mfma_f32_16x16x32_bf16 v[148:151], v[240:243], v[208:211], v[148:151]
	s_add_u32 s26, s26, 64
	s_addc_u32 s27, s27, 0
	s_add_u32 s28, s28, 64
	s_addc_u32 s29, s29, 0
	s_add_u32 s25, s25, 24576
	s_cmp_eq_u32 s25, 73728
	s_cselect_b32 s25, 0, s25
	s_add_u32 s30, s30, 24576
	s_cmp_eq_u32 s30, 73728
	s_cselect_b32 s30, 0, s30
	s_waitcnt vmcnt(6)
	s_waitcnt lgkmcnt(0)
	s_barrier
	v_add_u32_e32 v248, s30, v155
	v_add_u32_e32 v249, s30, v160
	v_mfma_f32_16x16x32_bf16 v[128:131], v[16:19], v[0:3], v[128:131]
	ds_read_b128 v[186:189], v248
	v_mfma_f32_16x16x32_bf16 v[96:99], v[16:19], v[4:7], v[96:99]
	ds_read_b128 v[212:215], v249 offset:8192
	v_mfma_f32_16x16x32_bf16 v[108:111], v[16:19], v[8:11], v[108:111]
	ds_read_b128 v[190:193], v248 offset:1024
	v_mfma_f32_16x16x32_bf16 v[132:135], v[16:19], v[12:15], v[132:135]
	ds_read_b128 v[216:219], v249 offset:9216
	v_mfma_f32_16x16x32_bf16 v[116:119], v[20:23], v[0:3], v[116:119]
	ds_read_b128 v[194:197], v248 offset:2048
	v_mfma_f32_16x16x32_bf16 v[92:95], v[20:23], v[4:7], v[92:95]
	ds_read_b128 v[220:223], v249 offset:10240
	v_mfma_f32_16x16x32_bf16 v[112:115], v[20:23], v[8:11], v[112:115]
	ds_read_b128 v[208:211], v248 offset:3072
	v_mfma_f32_16x16x32_bf16 v[136:139], v[20:23], v[12:15], v[136:139]
	ds_read_b128 v[224:227], v249 offset:11264
	v_mfma_f32_16x16x32_bf16 v[104:107], v[162:165], v[0:3], v[104:107]
	ds_read_b128 v[228:231], v249 offset:12288
	v_mfma_f32_16x16x32_bf16 v[88:91], v[162:165], v[4:7], v[88:91]
	ds_read_b128 v[232:235], v249 offset:13312
	v_mfma_f32_16x16x32_bf16 v[120:123], v[162:165], v[8:11], v[120:123]
	ds_read_b128 v[236:239], v249 offset:14336
	v_mfma_f32_16x16x32_bf16 v[140:143], v[162:165], v[12:15], v[140:143]
	ds_read_b128 v[240:243], v249 offset:15360
	v_mfma_f32_16x16x32_bf16 v[100:103], v[166:169], v[0:3], v[100:103]
	v_mfma_f32_16x16x32_bf16 v[84:87], v[166:169], v[4:7], v[84:87]
	v_mfma_f32_16x16x32_bf16 v[124:127], v[166:169], v[8:11], v[124:127]
	v_mfma_f32_16x16x32_bf16 v[144:147], v[166:169], v[12:15], v[144:147]
	v_mfma_f32_16x16x32_bf16 v[52:55], v[170:173], v[0:3], v[52:55]
	v_mfma_f32_16x16x32_bf16 v[36:39], v[170:173], v[4:7], v[36:39]
	v_mfma_f32_16x16x32_bf16 v[64:67], v[170:173], v[8:11], v[64:67]
	v_mfma_f32_16x16x32_bf16 v[76:79], v[170:173], v[12:15], v[76:79]
	v_mfma_f32_16x16x32_bf16 v[48:51], v[174:177], v[0:3], v[48:51]
	v_mfma_f32_16x16x32_bf16 v[32:35], v[174:177], v[4:7], v[32:35]
	v_mfma_f32_16x16x32_bf16 v[68:71], v[174:177], v[8:11], v[68:71]
	v_mfma_f32_16x16x32_bf16 v[72:75], v[174:177], v[12:15], v[72:75]
	v_mfma_f32_16x16x32_bf16 v[44:47], v[178:181], v[0:3], v[44:47]
	v_mfma_f32_16x16x32_bf16 v[28:31], v[178:181], v[4:7], v[28:31]
	v_mfma_f32_16x16x32_bf16 v[80:83], v[178:181], v[8:11], v[80:83]
	v_mfma_f32_16x16x32_bf16 v[60:63], v[178:181], v[12:15], v[60:63]
	v_mfma_f32_16x16x32_bf16 v[40:43], v[182:185], v[0:3], v[40:43]
	v_mfma_f32_16x16x32_bf16 v[24:27], v[182:185], v[4:7], v[24:27]
	v_mfma_f32_16x16x32_bf16 v[56:59], v[182:185], v[8:11], v[56:59]
	v_mfma_f32_16x16x32_bf16 v[148:151], v[182:185], v[12:15], v[148:151]
	s_add_u32 s30, s30, 24576
	s_cmp_eq_u32 s30, 73728
	s_cselect_b32 s30, 0, s30
	s_waitcnt vmcnt(0)
	s_waitcnt lgkmcnt(0)
	s_barrier
	v_add_u32_e32 v248, s30, v155
	v_add_u32_e32 v249, s30, v160
	v_mfma_f32_16x16x32_bf16 v[128:131], v[212:215], v[186:189], v[128:131]
	ds_read_b128 v[0:3], v248
	v_mfma_f32_16x16x32_bf16 v[96:99], v[212:215], v[190:193], v[96:99]
	ds_read_b128 v[16:19], v249 offset:8192
	v_mfma_f32_16x16x32_bf16 v[108:111], v[212:215], v[194:197], v[108:111]
	ds_read_b128 v[4:7], v248 offset:1024
	v_mfma_f32_16x16x32_bf16 v[132:135], v[212:215], v[208:211], v[132:135]
	ds_read_b128 v[20:23], v249 offset:9216
	v_mfma_f32_16x16x32_bf16 v[116:119], v[216:219], v[186:189], v[116:119]
	ds_read_b128 v[8:11], v248 offset:2048
	v_mfma_f32_16x16x32_bf16 v[92:95], v[216:219], v[190:193], v[92:95]
	ds_read_b128 v[162:165], v249 offset:10240
	v_mfma_f32_16x16x32_bf16 v[112:115], v[216:219], v[194:197], v[112:115]
	ds_read_b128 v[12:15], v248 offset:3072
	v_mfma_f32_16x16x32_bf16 v[136:139], v[216:219], v[208:211], v[136:139]
	ds_read_b128 v[166:169], v249 offset:11264
	v_mfma_f32_16x16x32_bf16 v[104:107], v[220:223], v[186:189], v[104:107]
	ds_read_b128 v[170:173], v249 offset:12288
	v_mfma_f32_16x16x32_bf16 v[88:91], v[220:223], v[190:193], v[88:91]
	ds_read_b128 v[174:177], v249 offset:13312
	v_mfma_f32_16x16x32_bf16 v[120:123], v[220:223], v[194:197], v[120:123]
	ds_read_b128 v[178:181], v249 offset:14336
	v_mfma_f32_16x16x32_bf16 v[140:143], v[220:223], v[208:211], v[140:143]
	ds_read_b128 v[182:185], v249 offset:15360
	v_mfma_f32_16x16x32_bf16 v[100:103], v[224:227], v[186:189], v[100:103]
	v_mfma_f32_16x16x32_bf16 v[84:87], v[224:227], v[190:193], v[84:87]
	v_mfma_f32_16x16x32_bf16 v[124:127], v[224:227], v[194:197], v[124:127]
	v_mfma_f32_16x16x32_bf16 v[144:147], v[224:227], v[208:211], v[144:147]
	v_mfma_f32_16x16x32_bf16 v[52:55], v[228:231], v[186:189], v[52:55]
	v_mfma_f32_16x16x32_bf16 v[36:39], v[228:231], v[190:193], v[36:39]
	v_mfma_f32_16x16x32_bf16 v[64:67], v[228:231], v[194:197], v[64:67]
	v_mfma_f32_16x16x32_bf16 v[76:79], v[228:231], v[208:211], v[76:79]
	v_mfma_f32_16x16x32_bf16 v[48:51], v[232:235], v[186:189], v[48:51]
	v_mfma_f32_16x16x32_bf16 v[32:35], v[232:235], v[190:193], v[32:35]
	v_mfma_f32_16x16x32_bf16 v[68:71], v[232:235], v[194:197], v[68:71]
	v_mfma_f32_16x16x32_bf16 v[72:75], v[232:235], v[208:211], v[72:75]
	v_mfma_f32_16x16x32_bf16 v[44:47], v[236:239], v[186:189], v[44:47]
	v_mfma_f32_16x16x32_bf16 v[28:31], v[236:239], v[190:193], v[28:31]
	v_mfma_f32_16x16x32_bf16 v[80:83], v[236:239], v[194:197], v[80:83]
	v_mfma_f32_16x16x32_bf16 v[60:63], v[236:239], v[208:211], v[60:63]
	v_mfma_f32_16x16x32_bf16 v[40:43], v[240:243], v[186:189], v[40:43]
	v_mfma_f32_16x16x32_bf16 v[24:27], v[240:243], v[190:193], v[24:27]
	v_mfma_f32_16x16x32_bf16 v[56:59], v[240:243], v[194:197], v[56:59]
	v_mfma_f32_16x16x32_bf16 v[148:151], v[240:243], v[208:211], v[148:151]
	s_add_u32 s30, s30, 24576
	s_cmp_eq_u32 s30, 73728
	s_cselect_b32 s30, 0, s30
	s_waitcnt lgkmcnt(0)
	s_barrier
	v_mfma_f32_16x16x32_bf16 v[128:131], v[16:19], v[0:3], v[128:131]
	v_mfma_f32_16x16x32_bf16 v[96:99], v[16:19], v[4:7], v[96:99]
	v_mfma_f32_16x16x32_bf16 v[108:111], v[16:19], v[8:11], v[108:111]
	v_mfma_f32_16x16x32_bf16 v[132:135], v[16:19], v[12:15], v[132:135]
	v_mfma_f32_16x16x32_bf16 v[116:119], v[20:23], v[0:3], v[116:119]
	v_mfma_f32_16x16x32_bf16 v[92:95], v[20:23], v[4:7], v[92:95]
	v_mfma_f32_16x16x32_bf16 v[112:115], v[20:23], v[8:11], v[112:115]
	v_mfma_f32_16x16x32_bf16 v[136:139], v[20:23], v[12:15], v[136:139]
	v_mfma_f32_16x16x32_bf16 v[104:107], v[162:165], v[0:3], v[104:107]
	v_mfma_f32_16x16x32_bf16 v[88:91], v[162:165], v[4:7], v[88:91]
	v_mfma_f32_16x16x32_bf16 v[120:123], v[162:165], v[8:11], v[120:123]
	v_mfma_f32_16x16x32_bf16 v[140:143], v[162:165], v[12:15], v[140:143]
	v_mfma_f32_16x16x32_bf16 v[100:103], v[166:169], v[0:3], v[100:103]
	v_mfma_f32_16x16x32_bf16 v[84:87], v[166:169], v[4:7], v[84:87]
	v_mfma_f32_16x16x32_bf16 v[124:127], v[166:169], v[8:11], v[124:127]
	v_mfma_f32_16x16x32_bf16 v[144:147], v[166:169], v[12:15], v[144:147]
	v_mfma_f32_16x16x32_bf16 v[52:55], v[170:173], v[0:3], v[52:55]
	v_mfma_f32_16x16x32_bf16 v[36:39], v[170:173], v[4:7], v[36:39]
	v_mfma_f32_16x16x32_bf16 v[64:67], v[170:173], v[8:11], v[64:67]
	v_mfma_f32_16x16x32_bf16 v[76:79], v[170:173], v[12:15], v[76:79]
	v_mfma_f32_16x16x32_bf16 v[48:51], v[174:177], v[0:3], v[48:51]
	v_mfma_f32_16x16x32_bf16 v[32:35], v[174:177], v[4:7], v[32:35]
	v_mfma_f32_16x16x32_bf16 v[68:71], v[174:177], v[8:11], v[68:71]
	v_mfma_f32_16x16x32_bf16 v[72:75], v[174:177], v[12:15], v[72:75]
	v_mfma_f32_16x16x32_bf16 v[44:47], v[178:181], v[0:3], v[44:47]
	v_mfma_f32_16x16x32_bf16 v[28:31], v[178:181], v[4:7], v[28:31]
	v_mfma_f32_16x16x32_bf16 v[80:83], v[178:181], v[8:11], v[80:83]
	v_mfma_f32_16x16x32_bf16 v[60:63], v[178:181], v[12:15], v[60:63]
	v_mfma_f32_16x16x32_bf16 v[40:43], v[182:185], v[0:3], v[40:43]
	v_mfma_f32_16x16x32_bf16 v[24:27], v[182:185], v[4:7], v[24:27]
	v_mfma_f32_16x16x32_bf16 v[56:59], v[182:185], v[8:11], v[56:59]
	v_mfma_f32_16x16x32_bf16 v[148:151], v[182:185], v[12:15], v[148:151]
	s_add_i32 s12, s12, s6
	s_add_i32 s11, s11, s9
	s_add_i32 s10, s10, s6
	s_cmpk_gt_u32 s12, 0x1ff
	s_cselect_b32 s23, 1, 0
	v_mov_b32 v250, v198
	s_nop 0
	v_and_b32_e32 v251, 15, v250
	v_bfe_u32 v156, v250, 4, 2
	v_bfe_u32 v157, v250, 6, 1
	v_bfe_u32 v158, v250, 7, 1
	v_lshl_add_u32 v158, v158, 6, s14
	v_add_u32_e32 v158, v158, v251
	v_lshl_add_u32 v157, v157, 7, s13
	v_lshl_add_u32 v159, v156, 2, v157
	v_lshlrev_b32_e32 v246, 6, v158
	v_lshlrev_b32_e32 v161, 1, v159
	v_lshl_add_u32 v244, v158, 13, v161
	v_and_b32_e32 v161, 1, v156
	v_mul_u32_u24_e32 v161, 24, v161
	v_add_u32_e32 v245, v244, v161
	s_mov_b32 s24, s92
	s_mov_b32 s25, s93
	global_load_dwordx4 v[0:3], v246, s[94:95]
	global_load_dwordx4 v[4:7], v246, s[94:95] offset:16
	global_load_dwordx4 v[8:11], v246, s[94:95] offset:32
	global_load_dwordx4 v[12:15], v246, s[94:95] offset:48
	global_load_dwordx4 v[16:19], v246, s[94:95] offset:1024
	global_load_dwordx4 v[20:23], v246, s[94:95] offset:1040
	global_load_dwordx4 v[162:165], v246, s[94:95] offset:1056
	global_load_dwordx4 v[166:169], v246, s[94:95] offset:1072
	global_load_dwordx4 v[170:173], v246, s[94:95] offset:2048
	global_load_dwordx4 v[174:177], v246, s[94:95] offset:2064
	global_load_dwordx4 v[178:181], v246, s[94:95] offset:2080
	global_load_dwordx4 v[182:185], v246, s[94:95] offset:2096
	global_load_dwordx4 v[186:189], v246, s[94:95] offset:3072
	global_load_dwordx4 v[190:193], v246, s[94:95] offset:3088
	global_load_dwordx4 v[194:197], v246, s[94:95] offset:3104
	global_load_dwordx4 v[208:211], v246, s[94:95] offset:3120
	s_waitcnt vmcnt(12)
	v_add_f32_e32 v247, v0, v1
	v_add_f32_e32 v248, v2, v3
	v_add_f32_e32 v247, v247, v248
	v_add_f32_e32 v249, v4, v5
	v_add_f32_e32 v248, v6, v7
	v_add_f32_e32 v249, v249, v248
	v_add_f32_e32 v247, v247, v249
	v_add_f32_e32 v249, v8, v9
	v_add_f32_e32 v248, v10, v11
	v_add_f32_e32 v249, v249, v248
	v_add_f32_e32 v247, v247, v249
	v_add_f32_e32 v249, v12, v13
	v_add_f32_e32 v248, v14, v15
	v_add_f32_e32 v249, v249, v248
	v_add_f32_e32 v247, v247, v249
	v_fmamk_f32 v247, v247, 0x3a800000, v199
	v_cmp_gt_f32_e32 vcc, s73, v247
	v_mul_f32_e32 v248, 0x4b800000, v247
	s_nop 0
	v_cndmask_b32_e32 v247, v247, v248, vcc
	v_rsq_f32_e32 v247, v247
	s_nop 0
	v_mul_f32_e32 v248, 0x45800000, v247
	v_cndmask_b32_e32 v247, v247, v248, vcc
	v_mul_f32_e32 v212, v128, v247
	v_mul_f32_e32 v249, v129, v247
	v_mul_f32_e32 v213, v130, v247
	v_mul_f32_e32 v248, v131, v247
	v_max_f32_e32 v212, 0, v212
	v_max_f32_e32 v249, 0, v249
	v_max_f32_e32 v213, 0, v213
	v_max_f32_e32 v248, 0, v248
	v_mul_f32_e32 v212, v212, v212
	v_mul_f32_e32 v249, v249, v249
	v_mul_f32_e32 v213, v213, v213
	v_mul_f32_e32 v248, v248, v248
	v_cvt_pk_bf16_f32 v212, v212, v249
	v_cvt_pk_bf16_f32 v213, v213, v248
	v_mul_f32_e32 v214, v116, v247
	v_mul_f32_e32 v249, v117, v247
	v_mul_f32_e32 v215, v118, v247
	v_mul_f32_e32 v248, v119, v247
	v_max_f32_e32 v214, 0, v214
	v_max_f32_e32 v249, 0, v249
	v_max_f32_e32 v215, 0, v215
	v_max_f32_e32 v248, 0, v248
	v_mul_f32_e32 v214, v214, v214
	v_mul_f32_e32 v249, v249, v249
	v_mul_f32_e32 v215, v215, v215
	v_mul_f32_e32 v248, v248, v248
	v_cvt_pk_bf16_f32 v214, v214, v249
	v_cvt_pk_bf16_f32 v215, v215, v248
	s_nop 1
	v_permlane16_swap_b32_e32 v212, v214
	v_permlane16_swap_b32_e32 v213, v215
	global_store_dwordx4 v245, v[212:215], s[24:25]
	v_mul_f32_e32 v216, v104, v247
	v_mul_f32_e32 v249, v105, v247
	v_mul_f32_e32 v217, v106, v247
	v_mul_f32_e32 v248, v107, v247
	v_max_f32_e32 v216, 0, v216
	v_max_f32_e32 v249, 0, v249
	v_max_f32_e32 v217, 0, v217
	v_max_f32_e32 v248, 0, v248
	v_mul_f32_e32 v216, v216, v216
	v_mul_f32_e32 v249, v249, v249
	v_mul_f32_e32 v217, v217, v217
	v_mul_f32_e32 v248, v248, v248
	v_cvt_pk_bf16_f32 v216, v216, v249
	v_cvt_pk_bf16_f32 v217, v217, v248
	v_mul_f32_e32 v218, v100, v247
	v_mul_f32_e32 v249, v101, v247
	v_mul_f32_e32 v219, v102, v247
	v_mul_f32_e32 v248, v103, v247
	v_max_f32_e32 v218, 0, v218
	v_max_f32_e32 v249, 0, v249
	v_max_f32_e32 v219, 0, v219
	v_max_f32_e32 v248, 0, v248
	v_mul_f32_e32 v218, v218, v218
	v_mul_f32_e32 v249, v249, v249
	v_mul_f32_e32 v219, v219, v219
	v_mul_f32_e32 v248, v248, v248
	v_cvt_pk_bf16_f32 v218, v218, v249
	v_cvt_pk_bf16_f32 v219, v219, v248
	s_nop 1
	v_permlane16_swap_b32_e32 v216, v218
	v_permlane16_swap_b32_e32 v217, v219
	global_store_dwordx4 v245, v[216:219], s[24:25] offset:64
	v_mul_f32_e32 v220, v52, v247
	v_mul_f32_e32 v249, v53, v247
	v_mul_f32_e32 v221, v54, v247
	v_mul_f32_e32 v248, v55, v247
	v_max_f32_e32 v220, 0, v220
	v_max_f32_e32 v249, 0, v249
	v_max_f32_e32 v221, 0, v221
	v_max_f32_e32 v248, 0, v248
	v_mul_f32_e32 v220, v220, v220
	v_mul_f32_e32 v249, v249, v249
	v_mul_f32_e32 v221, v221, v221
	v_mul_f32_e32 v248, v248, v248
	v_cvt_pk_bf16_f32 v220, v220, v249
	v_cvt_pk_bf16_f32 v221, v221, v248
	v_mul_f32_e32 v222, v48, v247
	v_mul_f32_e32 v249, v49, v247
	v_mul_f32_e32 v223, v50, v247
	v_mul_f32_e32 v248, v51, v247
	v_max_f32_e32 v222, 0, v222
	v_max_f32_e32 v249, 0, v249
	v_max_f32_e32 v223, 0, v223
	v_max_f32_e32 v248, 0, v248
	v_mul_f32_e32 v222, v222, v222
	v_mul_f32_e32 v249, v249, v249
	v_mul_f32_e32 v223, v223, v223
	v_mul_f32_e32 v248, v248, v248
	v_cvt_pk_bf16_f32 v222, v222, v249
	v_cvt_pk_bf16_f32 v223, v223, v248
	s_nop 1
	v_permlane16_swap_b32_e32 v220, v222
	v_permlane16_swap_b32_e32 v221, v223
	global_store_dwordx4 v245, v[220:223], s[24:25] offset:128
	v_mul_f32_e32 v224, v44, v247
	v_mul_f32_e32 v249, v45, v247
	v_mul_f32_e32 v225, v46, v247
	v_mul_f32_e32 v248, v47, v247
	v_max_f32_e32 v224, 0, v224
	v_max_f32_e32 v249, 0, v249
	v_max_f32_e32 v225, 0, v225
	v_max_f32_e32 v248, 0, v248
	v_mul_f32_e32 v224, v224, v224
	v_mul_f32_e32 v249, v249, v249
	v_mul_f32_e32 v225, v225, v225
	v_mul_f32_e32 v248, v248, v248
	v_cvt_pk_bf16_f32 v224, v224, v249
	v_cvt_pk_bf16_f32 v225, v225, v248
	v_mul_f32_e32 v226, v40, v247
	v_mul_f32_e32 v249, v41, v247
	v_mul_f32_e32 v227, v42, v247
	v_mul_f32_e32 v248, v43, v247
	v_max_f32_e32 v226, 0, v226
	v_max_f32_e32 v249, 0, v249
	v_max_f32_e32 v227, 0, v227
	v_max_f32_e32 v248, 0, v248
	v_mul_f32_e32 v226, v226, v226
	v_mul_f32_e32 v249, v249, v249
	v_mul_f32_e32 v227, v227, v227
	v_mul_f32_e32 v248, v248, v248
	v_cvt_pk_bf16_f32 v226, v226, v249
	v_cvt_pk_bf16_f32 v227, v227, v248
	s_nop 1
	v_permlane16_swap_b32_e32 v224, v226
	v_permlane16_swap_b32_e32 v225, v227
	global_store_dwordx4 v245, v[224:227], s[24:25] offset:192
	s_add_u32 s24, s24, 0x20000
	s_addc_u32 s25, s25, 0
	s_waitcnt vmcnt(12)
	v_add_f32_e32 v247, v16, v17
	v_add_f32_e32 v248, v18, v19
	v_add_f32_e32 v247, v247, v248
	v_add_f32_e32 v249, v20, v21
	v_add_f32_e32 v248, v22, v23
	v_add_f32_e32 v249, v249, v248
	v_add_f32_e32 v247, v247, v249
	v_add_f32_e32 v249, v162, v163
	v_add_f32_e32 v248, v164, v165
	v_add_f32_e32 v249, v249, v248
	v_add_f32_e32 v247, v247, v249
	v_add_f32_e32 v249, v166, v167
	v_add_f32_e32 v248, v168, v169
	v_add_f32_e32 v249, v249, v248
	v_add_f32_e32 v247, v247, v249
	v_fmamk_f32 v247, v247, 0x3a800000, v199
	v_cmp_gt_f32_e32 vcc, s73, v247
	v_mul_f32_e32 v248, 0x4b800000, v247
	s_nop 0
	v_cndmask_b32_e32 v247, v247, v248, vcc
	v_rsq_f32_e32 v247, v247
	s_nop 0
	v_mul_f32_e32 v248, 0x45800000, v247
	v_cndmask_b32_e32 v247, v247, v248, vcc
	v_mul_f32_e32 v228, v96, v247
	v_mul_f32_e32 v249, v97, v247
	v_mul_f32_e32 v229, v98, v247
	v_mul_f32_e32 v248, v99, v247
	v_max_f32_e32 v228, 0, v228
	v_max_f32_e32 v249, 0, v249
	v_max_f32_e32 v229, 0, v229
	v_max_f32_e32 v248, 0, v248
	v_mul_f32_e32 v228, v228, v228
	v_mul_f32_e32 v249, v249, v249
	v_mul_f32_e32 v229, v229, v229
	v_mul_f32_e32 v248, v248, v248
	v_cvt_pk_bf16_f32 v228, v228, v249
	v_cvt_pk_bf16_f32 v229, v229, v248
	v_mul_f32_e32 v230, v92, v247
	v_mul_f32_e32 v249, v93, v247
	v_mul_f32_e32 v231, v94, v247
	v_mul_f32_e32 v248, v95, v247
	v_max_f32_e32 v230, 0, v230
	v_max_f32_e32 v249, 0, v249
	v_max_f32_e32 v231, 0, v231
	v_max_f32_e32 v248, 0, v248
	v_mul_f32_e32 v230, v230, v230
	v_mul_f32_e32 v249, v249, v249
	v_mul_f32_e32 v231, v231, v231
	v_mul_f32_e32 v248, v248, v248
	v_cvt_pk_bf16_f32 v230, v230, v249
	v_cvt_pk_bf16_f32 v231, v231, v248
	s_nop 1
	v_permlane16_swap_b32_e32 v228, v230
	v_permlane16_swap_b32_e32 v229, v231
	global_store_dwordx4 v245, v[228:231], s[24:25]
	v_mul_f32_e32 v232, v88, v247
	v_mul_f32_e32 v249, v89, v247
	v_mul_f32_e32 v233, v90, v247
	v_mul_f32_e32 v248, v91, v247
	v_max_f32_e32 v232, 0, v232
	v_max_f32_e32 v249, 0, v249
	v_max_f32_e32 v233, 0, v233
	v_max_f32_e32 v248, 0, v248
	v_mul_f32_e32 v232, v232, v232
	v_mul_f32_e32 v249, v249, v249
	v_mul_f32_e32 v233, v233, v233
	v_mul_f32_e32 v248, v248, v248
	v_cvt_pk_bf16_f32 v232, v232, v249
	v_cvt_pk_bf16_f32 v233, v233, v248
	v_mul_f32_e32 v234, v84, v247
	v_mul_f32_e32 v249, v85, v247
	v_mul_f32_e32 v235, v86, v247
	v_mul_f32_e32 v248, v87, v247
	v_max_f32_e32 v234, 0, v234
	v_max_f32_e32 v249, 0, v249
	v_max_f32_e32 v235, 0, v235
	v_max_f32_e32 v248, 0, v248
	v_mul_f32_e32 v234, v234, v234
	v_mul_f32_e32 v249, v249, v249
	v_mul_f32_e32 v235, v235, v235
	v_mul_f32_e32 v248, v248, v248
	v_cvt_pk_bf16_f32 v234, v234, v249
	v_cvt_pk_bf16_f32 v235, v235, v248
	s_nop 1
	v_permlane16_swap_b32_e32 v232, v234
	v_permlane16_swap_b32_e32 v233, v235
	global_store_dwordx4 v245, v[232:235], s[24:25] offset:64
	v_mul_f32_e32 v236, v36, v247
	v_mul_f32_e32 v249, v37, v247
	v_mul_f32_e32 v237, v38, v247
	v_mul_f32_e32 v248, v39, v247
	v_max_f32_e32 v236, 0, v236
	v_max_f32_e32 v249, 0, v249
	v_max_f32_e32 v237, 0, v237
	v_max_f32_e32 v248, 0, v248
	v_mul_f32_e32 v236, v236, v236
	v_mul_f32_e32 v249, v249, v249
	v_mul_f32_e32 v237, v237, v237
	v_mul_f32_e32 v248, v248, v248
	v_cvt_pk_bf16_f32 v236, v236, v249
	v_cvt_pk_bf16_f32 v237, v237, v248
	v_mul_f32_e32 v238, v32, v247
	v_mul_f32_e32 v249, v33, v247
	v_mul_f32_e32 v239, v34, v247
	v_mul_f32_e32 v248, v35, v247
	v_max_f32_e32 v238, 0, v238
	v_max_f32_e32 v249, 0, v249
	v_max_f32_e32 v239, 0, v239
	v_max_f32_e32 v248, 0, v248
	v_mul_f32_e32 v238, v238, v238
	v_mul_f32_e32 v249, v249, v249
	v_mul_f32_e32 v239, v239, v239
	v_mul_f32_e32 v248, v248, v248
	v_cvt_pk_bf16_f32 v238, v238, v249
	v_cvt_pk_bf16_f32 v239, v239, v248
	s_nop 1
	v_permlane16_swap_b32_e32 v236, v238
	v_permlane16_swap_b32_e32 v237, v239
	global_store_dwordx4 v245, v[236:239], s[24:25] offset:128
	v_mul_f32_e32 v240, v28, v247
	v_mul_f32_e32 v249, v29, v247
	v_mul_f32_e32 v241, v30, v247
	v_mul_f32_e32 v248, v31, v247
	v_max_f32_e32 v240, 0, v240
	v_max_f32_e32 v249, 0, v249
	v_max_f32_e32 v241, 0, v241
	v_max_f32_e32 v248, 0, v248
	v_mul_f32_e32 v240, v240, v240
	v_mul_f32_e32 v249, v249, v249
	v_mul_f32_e32 v241, v241, v241
	v_mul_f32_e32 v248, v248, v248
	v_cvt_pk_bf16_f32 v240, v240, v249
	v_cvt_pk_bf16_f32 v241, v241, v248
	v_mul_f32_e32 v242, v24, v247
	v_mul_f32_e32 v249, v25, v247
	v_mul_f32_e32 v243, v26, v247
	v_mul_f32_e32 v248, v27, v247
	v_max_f32_e32 v242, 0, v242
	v_max_f32_e32 v249, 0, v249
	v_max_f32_e32 v243, 0, v243
	v_max_f32_e32 v248, 0, v248
	v_mul_f32_e32 v242, v242, v242
	v_mul_f32_e32 v249, v249, v249
	v_mul_f32_e32 v243, v243, v243
	v_mul_f32_e32 v248, v248, v248
	v_cvt_pk_bf16_f32 v242, v242, v249
	v_cvt_pk_bf16_f32 v243, v243, v248
	s_nop 1
	v_permlane16_swap_b32_e32 v240, v242
	v_permlane16_swap_b32_e32 v241, v243
	global_store_dwordx4 v245, v[240:243], s[24:25] offset:192
	s_add_u32 s24, s24, 0x20000
	s_addc_u32 s25, s25, 0
	s_waitcnt vmcnt(12)
	v_add_f32_e32 v247, v170, v171
	v_add_f32_e32 v248, v172, v173
	v_add_f32_e32 v247, v247, v248
	v_add_f32_e32 v249, v174, v175
	v_add_f32_e32 v248, v176, v177
	v_add_f32_e32 v249, v249, v248
	v_add_f32_e32 v247, v247, v249
	v_add_f32_e32 v249, v178, v179
	v_add_f32_e32 v248, v180, v181
	v_add_f32_e32 v249, v249, v248
	v_add_f32_e32 v247, v247, v249
	v_add_f32_e32 v249, v182, v183
	v_add_f32_e32 v248, v184, v185
	v_add_f32_e32 v249, v249, v248
	v_add_f32_e32 v247, v247, v249
	v_fmamk_f32 v247, v247, 0x3a800000, v199
	v_cmp_gt_f32_e32 vcc, s73, v247
	v_mul_f32_e32 v248, 0x4b800000, v247
	s_nop 0
	v_cndmask_b32_e32 v247, v247, v248, vcc
	v_rsq_f32_e32 v247, v247
	s_nop 0
	v_mul_f32_e32 v248, 0x45800000, v247
	v_cndmask_b32_e32 v247, v247, v248, vcc
	v_mul_f32_e32 v212, v108, v247
	v_mul_f32_e32 v249, v109, v247
	v_mul_f32_e32 v213, v110, v247
	v_mul_f32_e32 v248, v111, v247
	v_max_f32_e32 v212, 0, v212
	v_max_f32_e32 v249, 0, v249
	v_max_f32_e32 v213, 0, v213
	v_max_f32_e32 v248, 0, v248
	v_mul_f32_e32 v212, v212, v212
	v_mul_f32_e32 v249, v249, v249
	v_mul_f32_e32 v213, v213, v213
	v_mul_f32_e32 v248, v248, v248
	v_cvt_pk_bf16_f32 v212, v212, v249
	v_cvt_pk_bf16_f32 v213, v213, v248
	v_mul_f32_e32 v214, v112, v247
	v_mul_f32_e32 v249, v113, v247
	v_mul_f32_e32 v215, v114, v247
	v_mul_f32_e32 v248, v115, v247
	v_max_f32_e32 v214, 0, v214
	v_max_f32_e32 v249, 0, v249
	v_max_f32_e32 v215, 0, v215
	v_max_f32_e32 v248, 0, v248
	v_mul_f32_e32 v214, v214, v214
	v_mul_f32_e32 v249, v249, v249
	v_mul_f32_e32 v215, v215, v215
	v_mul_f32_e32 v248, v248, v248
	v_cvt_pk_bf16_f32 v214, v214, v249
	v_cvt_pk_bf16_f32 v215, v215, v248
	s_nop 1
	v_permlane16_swap_b32_e32 v212, v214
	v_permlane16_swap_b32_e32 v213, v215
	global_store_dwordx4 v245, v[212:215], s[24:25]
	v_mul_f32_e32 v216, v120, v247
	v_mul_f32_e32 v249, v121, v247
	v_mul_f32_e32 v217, v122, v247
	v_mul_f32_e32 v248, v123, v247
	v_max_f32_e32 v216, 0, v216
	v_max_f32_e32 v249, 0, v249
	v_max_f32_e32 v217, 0, v217
	v_max_f32_e32 v248, 0, v248
	v_mul_f32_e32 v216, v216, v216
	v_mul_f32_e32 v249, v249, v249
	v_mul_f32_e32 v217, v217, v217
	v_mul_f32_e32 v248, v248, v248
	v_cvt_pk_bf16_f32 v216, v216, v249
	v_cvt_pk_bf16_f32 v217, v217, v248
	v_mul_f32_e32 v218, v124, v247
	v_mul_f32_e32 v249, v125, v247
	v_mul_f32_e32 v219, v126, v247
	v_mul_f32_e32 v248, v127, v247
	v_max_f32_e32 v218, 0, v218
	v_max_f32_e32 v249, 0, v249
	v_max_f32_e32 v219, 0, v219
	v_max_f32_e32 v248, 0, v248
	v_mul_f32_e32 v218, v218, v218
	v_mul_f32_e32 v249, v249, v249
	v_mul_f32_e32 v219, v219, v219
	v_mul_f32_e32 v248, v248, v248
	v_cvt_pk_bf16_f32 v218, v218, v249
	v_cvt_pk_bf16_f32 v219, v219, v248
	s_nop 1
	v_permlane16_swap_b32_e32 v216, v218
	v_permlane16_swap_b32_e32 v217, v219
	global_store_dwordx4 v245, v[216:219], s[24:25] offset:64
	v_mul_f32_e32 v220, v64, v247
	v_mul_f32_e32 v249, v65, v247
	v_mul_f32_e32 v221, v66, v247
	v_mul_f32_e32 v248, v67, v247
	v_max_f32_e32 v220, 0, v220
	v_max_f32_e32 v249, 0, v249
	v_max_f32_e32 v221, 0, v221
	v_max_f32_e32 v248, 0, v248
	v_mul_f32_e32 v220, v220, v220
	v_mul_f32_e32 v249, v249, v249
	v_mul_f32_e32 v221, v221, v221
	v_mul_f32_e32 v248, v248, v248
	v_cvt_pk_bf16_f32 v220, v220, v249
	v_cvt_pk_bf16_f32 v221, v221, v248
	v_mul_f32_e32 v222, v68, v247
	v_mul_f32_e32 v249, v69, v247
	v_mul_f32_e32 v223, v70, v247
	v_mul_f32_e32 v248, v71, v247
	v_max_f32_e32 v222, 0, v222
	v_max_f32_e32 v249, 0, v249
	v_max_f32_e32 v223, 0, v223
	v_max_f32_e32 v248, 0, v248
	v_mul_f32_e32 v222, v222, v222
	v_mul_f32_e32 v249, v249, v249
	v_mul_f32_e32 v223, v223, v223
	v_mul_f32_e32 v248, v248, v248
	v_cvt_pk_bf16_f32 v222, v222, v249
	v_cvt_pk_bf16_f32 v223, v223, v248
	s_nop 1
	v_permlane16_swap_b32_e32 v220, v222
	v_permlane16_swap_b32_e32 v221, v223
	global_store_dwordx4 v245, v[220:223], s[24:25] offset:128
	v_mul_f32_e32 v224, v80, v247
	v_mul_f32_e32 v249, v81, v247
	v_mul_f32_e32 v225, v82, v247
	v_mul_f32_e32 v248, v83, v247
	v_max_f32_e32 v224, 0, v224
	v_max_f32_e32 v249, 0, v249
	v_max_f32_e32 v225, 0, v225
	v_max_f32_e32 v248, 0, v248
	v_mul_f32_e32 v224, v224, v224
	v_mul_f32_e32 v249, v249, v249
	v_mul_f32_e32 v225, v225, v225
	v_mul_f32_e32 v248, v248, v248
	v_cvt_pk_bf16_f32 v224, v224, v249
	v_cvt_pk_bf16_f32 v225, v225, v248
	v_mul_f32_e32 v226, v56, v247
	v_mul_f32_e32 v249, v57, v247
	v_mul_f32_e32 v227, v58, v247
	v_mul_f32_e32 v248, v59, v247
	v_max_f32_e32 v226, 0, v226
	v_max_f32_e32 v249, 0, v249
	v_max_f32_e32 v227, 0, v227
	v_max_f32_e32 v248, 0, v248
	v_mul_f32_e32 v226, v226, v226
	v_mul_f32_e32 v249, v249, v249
	v_mul_f32_e32 v227, v227, v227
	v_mul_f32_e32 v248, v248, v248
	v_cvt_pk_bf16_f32 v226, v226, v249
	v_cvt_pk_bf16_f32 v227, v227, v248
	s_nop 1
	v_permlane16_swap_b32_e32 v224, v226
	v_permlane16_swap_b32_e32 v225, v227
	global_store_dwordx4 v245, v[224:227], s[24:25] offset:192
	s_add_u32 s24, s24, 0x20000
	s_addc_u32 s25, s25, 0
	s_waitcnt vmcnt(12)
	v_add_f32_e32 v247, v186, v187
	v_add_f32_e32 v248, v188, v189
	v_add_f32_e32 v247, v247, v248
	v_add_f32_e32 v249, v190, v191
	v_add_f32_e32 v248, v192, v193
	v_add_f32_e32 v249, v249, v248
	v_add_f32_e32 v247, v247, v249
	v_add_f32_e32 v249, v194, v195
	v_add_f32_e32 v248, v196, v197
	v_add_f32_e32 v249, v249, v248
	v_add_f32_e32 v247, v247, v249
	v_add_f32_e32 v249, v208, v209
	v_add_f32_e32 v248, v210, v211
	v_add_f32_e32 v249, v249, v248
	v_add_f32_e32 v247, v247, v249
	v_fmamk_f32 v247, v247, 0x3a800000, v199
	v_cmp_gt_f32_e32 vcc, s73, v247
	v_mul_f32_e32 v248, 0x4b800000, v247
	s_nop 0
	v_cndmask_b32_e32 v247, v247, v248, vcc
	v_rsq_f32_e32 v247, v247
	s_nop 0
	v_mul_f32_e32 v248, 0x45800000, v247
	v_cndmask_b32_e32 v247, v247, v248, vcc
	v_mul_f32_e32 v228, v132, v247
	v_mul_f32_e32 v249, v133, v247
	v_mul_f32_e32 v229, v134, v247
	v_mul_f32_e32 v248, v135, v247
	v_max_f32_e32 v228, 0, v228
	v_max_f32_e32 v249, 0, v249
	v_max_f32_e32 v229, 0, v229
	v_max_f32_e32 v248, 0, v248
	v_mul_f32_e32 v228, v228, v228
	v_mul_f32_e32 v249, v249, v249
	v_mul_f32_e32 v229, v229, v229
	v_mul_f32_e32 v248, v248, v248
	v_cvt_pk_bf16_f32 v228, v228, v249
	v_cvt_pk_bf16_f32 v229, v229, v248
	v_mul_f32_e32 v230, v136, v247
	v_mul_f32_e32 v249, v137, v247
	v_mul_f32_e32 v231, v138, v247
	v_mul_f32_e32 v248, v139, v247
	v_max_f32_e32 v230, 0, v230
	v_max_f32_e32 v249, 0, v249
	v_max_f32_e32 v231, 0, v231
	v_max_f32_e32 v248, 0, v248
	v_mul_f32_e32 v230, v230, v230
	v_mul_f32_e32 v249, v249, v249
	v_mul_f32_e32 v231, v231, v231
	v_mul_f32_e32 v248, v248, v248
	v_cvt_pk_bf16_f32 v230, v230, v249
	v_cvt_pk_bf16_f32 v231, v231, v248
	s_nop 1
	v_permlane16_swap_b32_e32 v228, v230
	v_permlane16_swap_b32_e32 v229, v231
	global_store_dwordx4 v245, v[228:231], s[24:25]
	v_mul_f32_e32 v232, v140, v247
	v_mul_f32_e32 v249, v141, v247
	v_mul_f32_e32 v233, v142, v247
	v_mul_f32_e32 v248, v143, v247
	v_max_f32_e32 v232, 0, v232
	v_max_f32_e32 v249, 0, v249
	v_max_f32_e32 v233, 0, v233
	v_max_f32_e32 v248, 0, v248
	v_mul_f32_e32 v232, v232, v232
	v_mul_f32_e32 v249, v249, v249
	v_mul_f32_e32 v233, v233, v233
	v_mul_f32_e32 v248, v248, v248
	v_cvt_pk_bf16_f32 v232, v232, v249
	v_cvt_pk_bf16_f32 v233, v233, v248
	v_mul_f32_e32 v234, v144, v247
	v_mul_f32_e32 v249, v145, v247
	v_mul_f32_e32 v235, v146, v247
	v_mul_f32_e32 v248, v147, v247
	v_max_f32_e32 v234, 0, v234
	v_max_f32_e32 v249, 0, v249
	v_max_f32_e32 v235, 0, v235
	v_max_f32_e32 v248, 0, v248
	v_mul_f32_e32 v234, v234, v234
	v_mul_f32_e32 v249, v249, v249
	v_mul_f32_e32 v235, v235, v235
	v_mul_f32_e32 v248, v248, v248
	v_cvt_pk_bf16_f32 v234, v234, v249
	v_cvt_pk_bf16_f32 v235, v235, v248
	s_nop 1
	v_permlane16_swap_b32_e32 v232, v234
	v_permlane16_swap_b32_e32 v233, v235
	global_store_dwordx4 v245, v[232:235], s[24:25] offset:64
	v_mul_f32_e32 v236, v76, v247
	v_mul_f32_e32 v249, v77, v247
	v_mul_f32_e32 v237, v78, v247
	v_mul_f32_e32 v248, v79, v247
	v_max_f32_e32 v236, 0, v236
	v_max_f32_e32 v249, 0, v249
	v_max_f32_e32 v237, 0, v237
	v_max_f32_e32 v248, 0, v248
	v_mul_f32_e32 v236, v236, v236
	v_mul_f32_e32 v249, v249, v249
	v_mul_f32_e32 v237, v237, v237
	v_mul_f32_e32 v248, v248, v248
	v_cvt_pk_bf16_f32 v236, v236, v249
	v_cvt_pk_bf16_f32 v237, v237, v248
	v_mul_f32_e32 v238, v72, v247
	v_mul_f32_e32 v249, v73, v247
	v_mul_f32_e32 v239, v74, v247
	v_mul_f32_e32 v248, v75, v247
	v_max_f32_e32 v238, 0, v238
	v_max_f32_e32 v249, 0, v249
	v_max_f32_e32 v239, 0, v239
	v_max_f32_e32 v248, 0, v248
	v_mul_f32_e32 v238, v238, v238
	v_mul_f32_e32 v249, v249, v249
	v_mul_f32_e32 v239, v239, v239
	v_mul_f32_e32 v248, v248, v248
	v_cvt_pk_bf16_f32 v238, v238, v249
	v_cvt_pk_bf16_f32 v239, v239, v248
	s_nop 1
	v_permlane16_swap_b32_e32 v236, v238
	v_permlane16_swap_b32_e32 v237, v239
	global_store_dwordx4 v245, v[236:239], s[24:25] offset:128
	v_mul_f32_e32 v240, v60, v247
	v_mul_f32_e32 v249, v61, v247
	v_mul_f32_e32 v241, v62, v247
	v_mul_f32_e32 v248, v63, v247
	v_max_f32_e32 v240, 0, v240
	v_max_f32_e32 v249, 0, v249
	v_max_f32_e32 v241, 0, v241
	v_max_f32_e32 v248, 0, v248
	v_mul_f32_e32 v240, v240, v240
	v_mul_f32_e32 v249, v249, v249
	v_mul_f32_e32 v241, v241, v241
	v_mul_f32_e32 v248, v248, v248
	v_cvt_pk_bf16_f32 v240, v240, v249
	v_cvt_pk_bf16_f32 v241, v241, v248
	v_mul_f32_e32 v242, v148, v247
	v_mul_f32_e32 v249, v149, v247
	v_mul_f32_e32 v243, v150, v247
	v_mul_f32_e32 v248, v151, v247
	v_max_f32_e32 v242, 0, v242
	v_max_f32_e32 v249, 0, v249
	v_max_f32_e32 v243, 0, v243
	v_max_f32_e32 v248, 0, v248
	v_mul_f32_e32 v242, v242, v242
	v_mul_f32_e32 v249, v249, v249
	v_mul_f32_e32 v243, v243, v243
	v_mul_f32_e32 v248, v248, v248
	v_cvt_pk_bf16_f32 v242, v242, v249
	v_cvt_pk_bf16_f32 v243, v243, v248
	s_nop 1
	v_permlane16_swap_b32_e32 v240, v242
	v_permlane16_swap_b32_e32 v241, v243
	global_store_dwordx4 v245, v[240:243], s[24:25] offset:192
	s_add_u32 s24, s24, 0x20000
	s_addc_u32 s25, s25, 0
	s_cmp_lg_u32 s23, 0
	s_cbranch_scc0 .LBB0_13
